# per-segment priority in the differential-attention tile loop (MFMA segments high)
# speedup vs baseline: 1.0174x; 1.0021x over previous
; template <int DQK, int DV, int KW0, int MODE> ...
;     ...
;     {
;       bf16x8 kfa[DQK / 16], kfb[DQK / 16], qv[DQK / 16];
; #pragma unroll
;       for (int kk = 0; kk < DQK / 16; ++kk) {
;         kfa[kk] = *(const bf16x8*)(cur + r * (KS * 2) + kk * 32 + h * 16);
;         kfb[kk] = *(const bf16x8*)(cur + (32 + r) * (KS * 2) + kk * 32 + h * 16);
;         qv[kk] = QLDS ? *(const bf16x8*)(qbase + kk * 1024) : qf[kk];
;       }
; #pragma unroll
;       for (int kk = 0; kk < DQK / 16; ++kk) {
;         S0 = mfma32(kfa[kk], qv[kk], S0);
;         S1 = mfma32(kfb[kk], qv[kk], S1);
;       }
;       __builtin_amdgcn_sched_group_barrier(0x100, (QLDS ? 3 : 2) * (DQK / 16), 0);
;       __builtin_amdgcn_sched_group_barrier(0x008, 2 * (DQK / 16), 0);
;     }
;     if (MODE == 2) {
;       if (it >= 4) {
;         const int w = wlo + it - 4;
;         if (w < 2 || w > 3) {
;           const int kpos0 = (qn - 1) * 128 + 64 * w, qpos = qn * 128 + wid * 32 + r;
; #pragma unroll
;           for (int e = 0; e < 16; ++e) {
;             const int d0 = qpos - (kpos0 + crow(e, h)), d1 = d0 - 32;
;             if (d0 > 128 || d0 < -128) S0[e] = -1e30f;
;             if (d1 > 128 || d1 < -128) S1[e] = -1e30f;
;           }
;         }
;       }
;     }
;     float mx = S0[0];
; #pragma unroll
;     for (int e = 1; e < 16; ++e) mx = fmaxf(mx, S0[e]);
; #pragma unroll
;     for (int e = 0; e < 16; ++e) mx = fmaxf(mx, S1[e]);
;     mx = fmaxf(mx, __shfl_xor(mx, 32));
;     const float mn = fmaxf(m, mx);
;     const bool grow = __builtin_amdgcn_ballot_w64(mx > m) != 0ull;
;     const float alpha = __builtin_amdgcn_exp2f((m - mn) * c);
;     m = mn;
;     const float mc = mn * c;
;     float ps = 0.f;
; #pragma unroll
;     for (int e = 0; e < 16; ++e) { S0[e] = __builtin_amdgcn_exp2f(S0[e] * c - mc); ps += S0[e]; }
; #pragma unroll
;     for (int e = 0; e < 16; ++e) { S1[e] = __builtin_amdgcn_exp2f(S1[e] * c - mc); ps += S1[e]; }
;     if (grow) {
;       l *= alpha;
; #pragma unroll
;       for (int t = 0; t < DV / 32; ++t)
; #pragma unroll
;         for (int e = 0; e < 16; ++e) O[t][e] *= alpha;
;     }
;     ...
;       const unsigned vaddr = (unsigned)(size_t)(cur + KB) + (unsigned)((4 * h + ((lane & 15) >> 2)) * VSB + ((lane >> 4) & 1) * 32 + (lane & 3) * 8);
;       if (DV == 64) {
;         s16x4 R[8];
;     ...
;         PV_TILE64_(0); PV_TILE64_(1);
;     ...
;       } else {
;         s16x4 R[8];
.LBB0_41:
	s_bitcmp1_b32 s41, 0
	s_cselect_b32 s10, 0x7400, 0
	s_add_i32 s47, s10, 16
	v_add3_u32 v0, s47, v176, v177
	ds_read_b128 v[10:13], v0
	ds_read_b128 v[6:9], v182 offset:59392
	ds_read_b128 v[192:195], v0 offset:32
	ds_read_b128 v[2:5], v0 offset:4608
	ds_read_b128 v[218:221], v0 offset:4640
	ds_read_b128 v[222:225], v182 offset:60416
	ds_read_b128 v[226:229], v0 offset:64
	ds_read_b128 v[230:233], v0 offset:4672
	ds_read_b128 v[234:237], v182 offset:61440
	ds_read_b128 v[238:241], v0 offset:96
	ds_read_b128 v[242:245], v0 offset:4704
	ds_read_b128 v[246:249], v182 offset:62464
	s_setprio 1
	s_waitcnt lgkmcnt(10)
	v_mfma_f32_32x32x16_bf16 v[96:111], v[10:13], v[6:9], 0
	s_waitcnt lgkmcnt(6)
	v_mfma_f32_32x32x16_bf16 v[96:111], v[192:195], v[222:225], v[96:111]
	v_mfma_f32_32x32x16_bf16 v[80:95], v[2:5], v[6:9], 0
	v_max_f32_e32 v3, v183, v183
	s_waitcnt lgkmcnt(3)
	v_mfma_f32_32x32x16_bf16 v[96:111], v[226:229], v[234:237], v[96:111]
	v_mfma_f32_32x32x16_bf16 v[80:95], v[218:221], v[222:225], v[80:95]
	s_waitcnt lgkmcnt(0)
	v_mfma_f32_32x32x16_bf16 v[96:111], v[238:241], v[246:249], v[96:111]
	v_mfma_f32_32x32x16_bf16 v[80:95], v[230:233], v[234:237], v[80:95]
	s_nop 10
	v_max_f32_e32 v0, v97, v97
	v_max_f32_e32 v2, v96, v96
	v_max_f32_e32 v0, v2, v0
	v_max3_f32 v0, v0, v98, v99
	v_max3_f32 v0, v0, v100, v101
	v_max3_f32 v0, v0, v102, v103
	v_max3_f32 v0, v0, v104, v105
	v_mfma_f32_32x32x16_bf16 v[80:95], v[242:245], v[246:249], v[80:95]
	s_setprio 0
	v_max3_f32 v0, v0, v106, v107
	v_max3_f32 v0, v0, v108, v109
	v_max3_f32 v0, v0, v110, v111
	s_nop 8
	v_max3_f32 v0, v0, v80, v81
	v_max3_f32 v0, v0, v82, v83
	v_max3_f32 v0, v0, v84, v85
	v_max3_f32 v0, v0, v86, v87
	v_max3_f32 v0, v0, v88, v89
	v_max3_f32 v0, v0, v90, v91
	v_max3_f32 v0, v0, v92, v93
	v_max3_f32 v0, v0, v94, v95
	ds_bpermute_b32 v2, v115, v0
	s_waitcnt lgkmcnt(0)
	v_max_f32_e32 v2, v2, v2
	v_max_f32_e32 v0, v0, v2
	v_max_f32_e32 v3, v3, v0
	v_cmp_gt_f32_e32 vcc, v0, v183
	s_cbranch_vccz .LBB0_43
	v_sub_f32_e32 v0, v183, v3
	v_mul_f32_e32 v0, 0x3e38aa3b, v0
	v_exp_f32_e32 v0, v0
	s_nop 0
	v_pk_mul_f32 v[78:79], v[0:1], v[78:79] op_sel_hi:[0,1]
	v_pk_mul_f32 v[76:77], v[0:1], v[76:77] op_sel_hi:[0,1]
	v_pk_mul_f32 v[74:75], v[0:1], v[74:75] op_sel_hi:[0,1]
	v_pk_mul_f32 v[72:73], v[0:1], v[72:73] op_sel_hi:[0,1]
	v_pk_mul_f32 v[70:71], v[0:1], v[70:71] op_sel_hi:[0,1]
	v_pk_mul_f32 v[68:69], v[0:1], v[68:69] op_sel_hi:[0,1]
	v_pk_mul_f32 v[66:67], v[0:1], v[66:67] op_sel_hi:[0,1]
	v_pk_mul_f32 v[64:65], v[0:1], v[64:65] op_sel_hi:[0,1]
	v_pk_mul_f32 v[62:63], v[0:1], v[62:63] op_sel_hi:[0,1]
	v_pk_mul_f32 v[60:61], v[0:1], v[60:61] op_sel_hi:[0,1]
	v_pk_mul_f32 v[58:59], v[0:1], v[58:59] op_sel_hi:[0,1]
	v_pk_mul_f32 v[56:57], v[0:1], v[56:57] op_sel_hi:[0,1]
	v_pk_mul_f32 v[54:55], v[0:1], v[54:55] op_sel_hi:[0,1]
	v_pk_mul_f32 v[52:53], v[0:1], v[52:53] op_sel_hi:[0,1]
	v_pk_mul_f32 v[50:51], v[0:1], v[50:51] op_sel_hi:[0,1]
	v_pk_mul_f32 v[48:49], v[0:1], v[48:49] op_sel_hi:[0,1]
	v_pk_mul_f32 v[46:47], v[0:1], v[46:47] op_sel_hi:[0,1]
	v_pk_mul_f32 v[44:45], v[0:1], v[44:45] op_sel_hi:[0,1]
	v_pk_mul_f32 v[42:43], v[0:1], v[42:43] op_sel_hi:[0,1]
	v_pk_mul_f32 v[40:41], v[0:1], v[40:41] op_sel_hi:[0,1]
	v_pk_mul_f32 v[38:39], v[0:1], v[38:39] op_sel_hi:[0,1]
	v_pk_mul_f32 v[36:37], v[0:1], v[36:37] op_sel_hi:[0,1]
	v_pk_mul_f32 v[34:35], v[0:1], v[34:35] op_sel_hi:[0,1]
	v_pk_mul_f32 v[32:33], v[0:1], v[32:33] op_sel_hi:[0,1]
	v_pk_mul_f32 v[30:31], v[0:1], v[30:31] op_sel_hi:[0,1]
	v_pk_mul_f32 v[28:29], v[0:1], v[28:29] op_sel_hi:[0,1]
	v_pk_mul_f32 v[26:27], v[0:1], v[26:27] op_sel_hi:[0,1]
	v_pk_mul_f32 v[24:25], v[0:1], v[24:25] op_sel_hi:[0,1]
	v_pk_mul_f32 v[22:23], v[0:1], v[22:23] op_sel_hi:[0,1]
	v_pk_mul_f32 v[20:21], v[0:1], v[20:21] op_sel_hi:[0,1]
	v_pk_mul_f32 v[18:19], v[0:1], v[18:19] op_sel_hi:[0,1]
	v_pk_mul_f32 v[16:17], v[0:1], v[16:17] op_sel_hi:[0,1]
	v_mul_f32_e32 v145, v145, v0
.LBB0_43:
	v_mov_b32_e32 v2, v111
	v_pk_mul_f32 v[184:185], v[2:3], s[88:89] op_sel_hi:[1,0]
	s_addk_i32 s47, 0x2400
	v_fma_f32 v4, v98, s88, -v185
	v_exp_f32_e32 v111, v4
	v_fma_f32 v4, v99, s88, -v185
	v_exp_f32_e32 v183, v4
	v_fma_f32 v4, v100, s88, -v185
	v_exp_f32_e32 v100, v4
	v_fma_f32 v4, v101, s88, -v185
	v_exp_f32_e32 v101, v4
	v_fma_f32 v4, v102, s88, -v185
	v_exp_f32_e32 v102, v4
	v_fma_f32 v4, v103, s88, -v185
	v_exp_f32_e32 v103, v4
	v_fma_f32 v4, v104, s88, -v185
	v_exp_f32_e32 v104, v4
	v_fma_f32 v4, v105, s88, -v185
	v_exp_f32_e32 v105, v4
	v_fma_f32 v4, v106, s88, -v185
	v_exp_f32_e32 v106, v4
	v_fma_f32 v4, v107, s88, -v185
	v_exp_f32_e32 v107, v4
	v_fma_f32 v4, v108, s88, -v185
	v_exp_f32_e32 v108, v4
	v_fma_f32 v4, v109, s88, -v185
	v_exp_f32_e32 v109, v4
	v_fma_f32 v4, v110, s88, -v185
	v_exp_f32_e32 v110, v4
	v_sub_f32_e32 v4, v184, v185
	v_exp_f32_e32 v184, v4
	v_fma_f32 v4, v80, s88, -v185
	v_exp_f32_e32 v189, v4
	v_fma_f32 v4, v81, s88, -v185
	v_exp_f32_e32 v192, v4
	v_fma_f32 v4, v82, s88, -v185
	v_exp_f32_e32 v193, v4
	v_fma_f32 v4, v83, s88, -v185
	v_exp_f32_e32 v194, v4
	v_fma_f32 v4, v84, s88, -v185
	v_exp_f32_e32 v195, v4
	v_fma_f32 v4, v85, s88, -v185
	v_fma_f32 v0, v96, s88, -v185
	v_fma_f32 v2, v97, s88, -v185
	v_exp_f32_e32 v196, v4
	v_fma_f32 v4, v86, s88, -v185
	v_exp_f32_e32 v0, v0
	v_exp_f32_e32 v2, v2
	v_exp_f32_e32 v197, v4
	v_fma_f32 v4, v87, s88, -v185
	v_exp_f32_e32 v218, v4
	v_fma_f32 v4, v88, s88, -v185
	v_exp_f32_e32 v219, v4
	v_fma_f32 v4, v89, s88, -v185
	v_exp_f32_e32 v220, v4
	v_fma_f32 v4, v90, s88, -v185
	v_exp_f32_e32 v221, v4
	v_cvt_pk_bf16_f32 v4, v0, v2
	v_cvt_pk_bf16_f32 v5, v111, v183
	v_cvt_pk_bf16_f32 v6, v100, v101
	v_cvt_pk_bf16_f32 v7, v102, v103
	v_add_u32_e32 v222, s47, v178
	s_setprio 1
	ds_read_b64_tr_b16 v[84:85], v222 offset:0
	ds_read_b64_tr_b16 v[86:87], v222 offset:2560
	ds_read_b64_tr_b16 v[80:81], v222 offset:5120
	ds_read_b64_tr_b16 v[82:83], v222 offset:7680
	ds_read_b64_tr_b16 v[12:13], v222 offset:10240
	ds_read_b64_tr_b16 v[14:15], v222 offset:12800
	ds_read_b64_tr_b16 v[8:9], v222 offset:15360
	ds_read_b64_tr_b16 v[10:11], v222 offset:17920
	s_waitcnt lgkmcnt(0)
; #define GAS __attribute__((address_space(1)))
; template <int DQK, int DV, int KW0, int WHICH> ...
;     ...
;   for (int i = 0; i < NKC; ++i) {
;     const int id = tid + 256 * i, key = id / KCH, ch = id % KCH;
;     const bf16_t* src;
;     if constexpr (KW0 == DQK) src = (const bf16_t*)((const char*)(k0p + (size_t)krow * ldk0) + (unsigned)((key * ldk0 + ch * 8) * 2));
;     else src = (ch * 8 < KW0) ? (k0p + (size_t)(krow + key) * ldk0 + ch * 8) : (k1p + (size_t)(krow + key) * ldk1 + (ch * 8 - KW0));
;     kreg[i] = *(const GAS u32x4*)src;
;   }
;   if (WHICH & 2)
; #pragma unroll
;   for (int u = 0; u < NVU; ++u) {
;     const int id = tid + 256 * u, kp = id / VCH, ch = id % VCH;
;     const char* vb = (const char*)(vp + (size_t)krow * ldv);
;     vreg[u][0] = *(const GAS u32x4*)(vb + (unsigned)((2 * kp * ldv + ch * 8) * 2));
;     vreg[u][1] = *(const GAS u32x4*)(vb + (unsigned)(((2 * kp + 1) * ldv + ch * 8) * 2));
;   }
; }
; template <int DQK, int DV>
; DI void attn_sstore(const u32x4 (&kreg)[(64 * (DQK / 8)) / 256], const u32x4 (&vreg)[(32 * (DV / 8)) / 256][2], char* stage, int tid) {
; template <int DQK, int DV, int KW0, int MODE> ...
;     ...
;     bf16x8 pf[2][2];
; #pragma unroll
;     for (int s = 0; s < 2; ++s) {
;       u32x4 w0, w1;
;       w0.x = pk2(S0[8 * s + 0], S0[8 * s + 1]); w0.y = pk2(S0[8 * s + 2], S0[8 * s + 3]); w0.z = pk2(S0[8 * s + 4], S0[8 * s + 5]); w0.w = pk2(S0[8 * s + 6], S0[8 * s + 7]);
;       w1.x = pk2(S1[8 * s + 0], S1[8 * s + 1]); w1.y = pk2(S1[8 * s + 2], S1[8 * s + 3]); w1.z = pk2(S1[8 * s + 4], S1[8 * s + 5]); w1.w = pk2(S1[8 * s + 6], S1[8 * s + 7]);
;       pf[0][s] = __builtin_bit_cast(bf16x8, w0); pf[1][s] = __builtin_bit_cast(bf16x8, w1);
;     }
;     {
;       const unsigned vaddr = (unsigned)(size_t)(cur + KB) + (unsigned)((4 * h + ((lane & 15) >> 2)) * VSB + ((lane >> 4) & 1) * 32 + (lane & 3) * 8);
;       if (DV == 64) {
;         s16x4 R[8];
;     ...
;         PV_TILE64_(0); PV_TILE64_(1);
;     ...
;       } else {
;         s16x4 R[8];
;     ...
;         PV_TILE_(0); PV_TILE_(1); PV_TILE_(2); PV_TILE_(3);
;     ...
;       }
;     }
;     if (DV > 64) { __builtin_amdgcn_sched_barrier(0); if (more) attn_gload<DQK, DV, KW0, 3>(kreg, vreg, k0p, ldk0, k1p, ldk1, vp, ldv, key_tile_row<MODE>(it + 1, b, qn, wlo), tid); }
;     if (more) attn_sstore<DQK, DV>(kreg, vreg, smem + ((it + 1) & 1) * STG, tid);
;     __syncthreads();
	v_fma_f32 v88, v91, s88, -v185
	v_mfma_f32_32x32x16_bf16 v[64:79], v[84:87], v[4:7], v[64:79]
	v_fma_f32 v84, v92, s88, -v185
	v_exp_f32_e32 v224, v84
	v_cvt_pk_bf16_f32 v84, v104, v105
	v_cvt_pk_bf16_f32 v85, v106, v107
	v_cvt_pk_bf16_f32 v86, v108, v109
	v_cvt_pk_bf16_f32 v87, v110, v184
	v_exp_f32_e32 v223, v88
	v_fma_f32 v88, v94, s88, -v185
	v_mfma_f32_32x32x16_bf16 v[64:79], v[80:83], v[84:87], v[64:79]
	v_fma_f32 v80, v93, s88, -v185
	v_exp_f32_e32 v225, v80
	v_cvt_pk_bf16_f32 v80, v189, v192
	v_cvt_pk_bf16_f32 v81, v193, v194
	v_cvt_pk_bf16_f32 v82, v195, v196
	v_cvt_pk_bf16_f32 v83, v197, v218
	v_exp_f32_e32 v226, v88
	v_add_f32_e32 v0, 0, v0
	v_mfma_f32_32x32x16_bf16 v[64:79], v[12:15], v[80:83], v[64:79]
	v_fma_f32 v12, v95, s88, -v185
	v_exp_f32_e32 v185, v12
	v_cvt_pk_bf16_f32 v12, v219, v220
	v_cvt_pk_bf16_f32 v13, v221, v223
	v_cvt_pk_bf16_f32 v14, v224, v225
	v_cvt_pk_bf16_f32 v15, v226, v185
	v_add_f32_e32 v0, v2, v0
	v_add_f32_e32 v0, v111, v0
	v_mfma_f32_32x32x16_bf16 v[64:79], v[8:11], v[12:15], v[64:79]
	ds_read_b64_tr_b16 v[96:97], v222 offset:64
	ds_read_b64_tr_b16 v[98:99], v222 offset:2624
	ds_read_b64_tr_b16 v[92:93], v222 offset:5184
	ds_read_b64_tr_b16 v[94:95], v222 offset:7744
	ds_read_b64_tr_b16 v[88:89], v222 offset:10304
	ds_read_b64_tr_b16 v[90:91], v222 offset:12864
	ds_read_b64_tr_b16 v[8:9], v222 offset:15424
	ds_read_b64_tr_b16 v[10:11], v222 offset:17984
	s_waitcnt lgkmcnt(0)
	v_add_f32_e32 v0, v183, v0
	v_add_f32_e32 v0, v100, v0
	v_add_f32_e32 v0, v101, v0
	v_add_f32_e32 v0, v102, v0
	v_add_f32_e32 v0, v103, v0
	v_add_f32_e32 v0, v104, v0
	v_mfma_f32_32x32x16_bf16 v[48:63], v[96:99], v[4:7], v[48:63]
	v_add_f32_e32 v0, v105, v0
	v_add_f32_e32 v0, v106, v0
	v_add_f32_e32 v0, v107, v0
	v_add_f32_e32 v0, v108, v0
	v_add_f32_e32 v0, v109, v0
	v_add_f32_e32 v0, v110, v0
	v_add_f32_e32 v0, v184, v0
	v_mfma_f32_32x32x16_bf16 v[48:63], v[92:95], v[84:87], v[48:63]
	v_add_f32_e32 v0, v189, v0
	v_add_f32_e32 v0, v192, v0
	v_add_f32_e32 v0, v193, v0
	v_add_f32_e32 v0, v194, v0
	v_add_f32_e32 v0, v195, v0
	v_add_f32_e32 v0, v196, v0
	v_add_f32_e32 v0, v197, v0
	v_mfma_f32_32x32x16_bf16 v[48:63], v[88:91], v[80:83], v[48:63]
	v_add_f32_e32 v0, v218, v0
	v_add_f32_e32 v0, v219, v0
	v_add_f32_e32 v0, v220, v0
	v_add_f32_e32 v0, v221, v0
	v_add_f32_e32 v0, v223, v0
	v_add_f32_e32 v0, v224, v0
	v_add_f32_e32 v0, v225, v0
	v_mfma_f32_32x32x16_bf16 v[48:63], v[8:11], v[12:15], v[48:63]
	ds_read_b64_tr_b16 v[96:97], v222 offset:128
	ds_read_b64_tr_b16 v[98:99], v222 offset:2688
	ds_read_b64_tr_b16 v[92:93], v222 offset:5248
	ds_read_b64_tr_b16 v[94:95], v222 offset:7808
	ds_read_b64_tr_b16 v[88:89], v222 offset:10368
	ds_read_b64_tr_b16 v[90:91], v222 offset:12928
	ds_read_b64_tr_b16 v[8:9], v222 offset:15488
	ds_read_b64_tr_b16 v[10:11], v222 offset:18048
	s_waitcnt lgkmcnt(0)
	v_add_f32_e32 v0, v226, v0
	v_add_f32_e32 v0, v185, v0
	s_add_i32 s47, s41, 1
	v_add_f32_e32 v145, v0, v145
	v_mfma_f32_32x32x16_bf16 v[32:47], v[96:99], v[4:7], v[32:47]
	v_mfma_f32_32x32x16_bf16 v[32:47], v[92:95], v[84:87], v[32:47]
	v_mfma_f32_32x32x16_bf16 v[32:47], v[88:91], v[80:83], v[32:47]
	v_mfma_f32_32x32x16_bf16 v[32:47], v[8:11], v[12:15], v[32:47]
	ds_read_b64_tr_b16 v[96:97], v222 offset:192
	ds_read_b64_tr_b16 v[98:99], v222 offset:2752
	ds_read_b64_tr_b16 v[92:93], v222 offset:5312
	ds_read_b64_tr_b16 v[94:95], v222 offset:7872
	ds_read_b64_tr_b16 v[88:89], v222 offset:10432
	ds_read_b64_tr_b16 v[90:91], v222 offset:12992
	ds_read_b64_tr_b16 v[8:9], v222 offset:15552
	ds_read_b64_tr_b16 v[10:11], v222 offset:18112
	s_waitcnt lgkmcnt(0)
	s_nop 0
	v_mfma_f32_32x32x16_bf16 v[16:31], v[96:99], v[4:7], v[16:31]
	v_mfma_f32_32x32x16_bf16 v[16:31], v[92:95], v[84:87], v[16:31]
	v_mfma_f32_32x32x16_bf16 v[16:31], v[88:91], v[80:83], v[16:31]
	v_mfma_f32_32x32x16_bf16 v[16:31], v[8:11], v[12:15], v[16:31]
	s_setprio 0
	s_cmp_lt_u32 s41, 3
	s_cselect_b32 s10, 8, 11
	s_mov_b32 s11, 0x10000
	s_cselect_b32 s11, s11, 0xffffff00
	s_lshl_b32 s10, s23, s10
	s_add_i32 s11, s11, s10
	s_add_i32 s10, s40, s11
	s_mul_hi_i32 s11, s10, 0x1200
	s_mulk_i32 s10, 0x1200
	s_add_u32 s56, s16, s10
	s_addc_u32 s57, s17, s11
	v_lshl_add_u64 v[4:5], s[56:57], 0, v[120:121]
	v_lshl_add_u64 v[8:9], s[56:57], 0, v[122:123]
	s_add_u32 s56, s44, s10
	global_load_dwordx4 v[4:7], v[4:5], off
	s_addc_u32 s57, s45, s11
	global_load_dwordx4 v[8:11], v[8:9], off
	v_lshl_add_u64 v[12:13], s[56:57], 0, v[124:125]
	global_load_dwordx4 v[12:15], v[12:13], off
	v_lshl_add_u64 v[80:81], s[56:57], 0, v[126:127]
	v_lshl_add_u64 v[84:85], s[56:57], 0, v[128:129]
	global_load_dwordx4 v[80:83], v[80:81], off
	v_lshl_add_u64 v[88:89], s[56:57], 0, v[138:139]
	global_load_dwordx4 v[84:87], v[84:85], off
	s_bitcmp1_b32 s47, 0
	global_load_dwordx4 v[88:91], v[88:89], off
	s_cselect_b32 s10, 0x7400, 0
	s_add_i32 s41, s10, 16
	v_add3_u32 v0, s41, v168, v169
	s_add_i32 s40, s40, 64
	s_cmp_eq_u32 s46, s47
	s_waitcnt vmcnt(5)
	ds_write_b128 v0, v[4:7]
	v_add3_u32 v0, s41, v170, v171
	s_waitcnt vmcnt(4)
	ds_write_b128 v0, v[8:11]
	v_add3_u32 v0, s41, v172, v173
	s_waitcnt vmcnt(3)
	ds_write_b128 v0, v[12:15] offset:9216
	s_waitcnt vmcnt(2)
	ds_write_b128 v0, v[80:83] offset:9536
	v_add3_u32 v0, s41, v174, v175
	s_waitcnt vmcnt(1)
	ds_write_b128 v0, v[84:87] offset:9216
	s_waitcnt vmcnt(0)
	ds_write_b128 v0, v[88:91] offset:9536
	s_waitcnt lgkmcnt(0)
	s_barrier
	s_cbranch_scc1 .LBB0_45
	v_mov_b32_e32 v183, v3
	s_mov_b32 s41, s47
	s_branch .LBB0_41
